# prologue-b row items: the four (norm gain, scale) table chunks are fetched together (one wait) instead of four load-then-wait round trips
# baseline (speedup 1.0000x reference)
; DI void phase0b(const Params& p, char* lds) {
;     ...
;       const int rb = (it - N_B) * 64;
;       const int modrow = rb < NLAT ? rb / SEQ : 16;
;       const float* scp = p.mod + (size_t)modrow * 3072 + 1024;
;       f32x4 gsv[4];
; #pragma unroll
;       for (int pp = 0; pp < 4; ++pp) {
;         const int k = pp * 256 + lane * 4;
;         const f32x4 g = *(const f32x4*)(p.norm_gain + k);
;         const f32x4 sc = *(const f32x4*)(scp + k);
; #pragma unroll
;         for (int j = 0; j < 4; ++j) gsv[pp][j] = g[j] * (1.f + sc[j]);
;       }
; #pragma unroll
;       for (int qb = 0; qb < 2; ++qb) {
;         f32x4 xv[4][4];
; #pragma unroll
;         for (int q = 0; q < 4; ++q) {
;           const int row = rb + w * 8 + qb * 4 + q;
;           const float* src = row < NLAT ? p.x + (size_t)row * DM : p.ctx + (size_t)(row - NLAT) * DM;
; #pragma unroll
;           for (int pp = 0; pp < 4; ++pp) xv[q][pp] = *(const f32x4*)(src + pp * 256 + lane * 4);
.LBB0_16:
	s_cmpk_gt_i32 s24, 0xaf
	s_mov_b64 s[2:3], -1
	s_cbranch_scc0 .LBB0_34
	s_lshl_b32 s0, s24, 6
	s_add_i32 s8, s0, 0xffffd400
	s_lshr_b32 s0, s8, 11
	s_cmpk_lt_u32 s8, 0x8000
	s_mulk_i32 s0, 0xc00
	s_cselect_b32 s0, s0, 0xc000
	s_lshl_b64 s[2:3], s[0:1], 2
	v_readlane_b32 s16, v254, 59
	v_readlane_b32 s17, v254, 60
	s_add_u32 s0, s16, s2
	s_addc_u32 s3, s17, s3
	s_add_u32 s2, s0, 0x1000
	s_addc_u32 s3, s3, 0
	global_load_dwordx4 v[6:9], v88, s[2:3]
	global_load_dwordx4 v[2:5], v[84:85], off
	global_load_dwordx4 v[50:53], v[84:85], off offset:1024
	global_load_dwordx4 v[54:57], v105, s[2:3]
	global_load_dwordx4 v[58:61], v[84:85], off offset:2048
	global_load_dwordx4 v[62:65], v106, s[2:3]
	global_load_dwordx4 v[34:37], v[84:85], off offset:3072
	global_load_dwordx4 v[38:41], v107, s[2:3]
	v_add_u32_e32 v90, s8, v104
	v_readlane_b32 s36, v254, 9
	v_cmp_gt_i32_e32 vcc, s85, v90
	v_add_u32_e32 v0, 0xffff8000, v90
	v_ashrrev_i32_e32 v91, 31, v90
	v_readlane_b32 s37, v254, 10
	v_readlane_b32 s40, v254, 13
	v_readlane_b32 s41, v254, 14
	v_mov_b32_e32 v10, s37
	v_mov_b32_e32 v11, s40
	v_mov_b32_e32 v12, s36
	v_mov_b32_e32 v89, v1
	v_or_b32_e32 v96, 1, v90
	v_ashrrev_i32_e32 v97, 31, v96
	v_or_b32_e32 v94, 2, v90
	v_ashrrev_i32_e32 v95, 31, v94
	v_or_b32_e32 v92, 3, v90
	v_ashrrev_i32_e32 v93, 31, v92
	v_lshlrev_b64 v[98:99], 11, v[90:91]
	v_readlane_b32 s18, v254, 61
	v_readlane_b32 s19, v254, 62
	v_readlane_b32 s38, v254, 11
	v_readlane_b32 s39, v254, 12
	v_readlane_b32 s42, v254, 15
	v_readlane_b32 s43, v254, 16
	v_readlane_b32 s44, v254, 17
	v_readlane_b32 s45, v254, 18
	v_readlane_b32 s46, v254, 19
	v_readlane_b32 s47, v254, 20
	v_readlane_b32 s48, v254, 21
	v_readlane_b32 s49, v254, 22
	v_readlane_b32 s50, v254, 23
	v_readlane_b32 s51, v254, 24
	s_waitcnt vmcnt(7)
	v_pk_add_f32 v[6:7], v[6:7], 1.0 op_sel_hi:[1,0]
	s_waitcnt vmcnt(6)
	v_pk_mul_f32 v[68:69], v[2:3], v[6:7]
	v_pk_add_f32 v[2:3], v[8:9], 1.0 op_sel_hi:[1,0]
	s_nop 0
	v_pk_mul_f32 v[66:67], v[4:5], v[2:3]
	s_waitcnt vmcnt(4)
	v_pk_add_f32 v[54:55], v[54:55], 1.0 op_sel_hi:[1,0]
	s_nop 0
	v_pk_mul_f32 v[70:71], v[50:51], v[54:55]
	v_pk_add_f32 v[56:57], v[56:57], 1.0 op_sel_hi:[1,0]
	s_nop 0
	v_pk_mul_f32 v[72:73], v[52:53], v[56:57]
	s_waitcnt vmcnt(2)
	v_pk_add_f32 v[62:63], v[62:63], 1.0 op_sel_hi:[1,0]
	s_nop 0
	v_pk_mul_f32 v[76:77], v[58:59], v[62:63]
	v_pk_add_f32 v[64:65], v[64:65], 1.0 op_sel_hi:[1,0]
	s_nop 0
	v_pk_mul_f32 v[74:75], v[60:61], v[64:65]
	s_waitcnt vmcnt(0)
	v_pk_add_f32 v[38:39], v[38:39], 1.0 op_sel_hi:[1,0]
	s_nop 0
	v_pk_mul_f32 v[80:81], v[34:35], v[38:39]
	v_pk_add_f32 v[40:41], v[40:41], 1.0 op_sel_hi:[1,0]
	s_nop 0
	v_pk_mul_f32 v[78:79], v[36:37], v[40:41]
	v_cndmask_b32_e32 v3, 0, v91, vcc
	v_cndmask_b32_e32 v2, v0, v90, vcc
	v_mov_b32_e32 v0, s41
	v_cndmask_b32_e32 v5, v0, v10, vcc
	v_cndmask_b32_e32 v4, v11, v12, vcc
	v_lshlrev_b64 v[2:3], 12, v[2:3]
	v_lshl_add_u64 v[2:3], v[4:5], 0, v[2:3]
	v_lshl_add_u64 v[2:3], v[2:3], 0, v[88:89]
	global_load_dwordx4 v[62:65], v[2:3], off
	global_load_dwordx4 v[58:61], v[2:3], off offset:1024
	global_load_dwordx4 v[54:57], v[2:3], off offset:2048
	global_load_dwordx4 v[50:53], v[2:3], off offset:3072
	v_cmp_gt_i32_e32 vcc, s85, v96
	v_add_u32_e32 v2, 0xffff8001, v90
	s_nop 0
	v_cndmask_b32_e32 v3, 0, v97, vcc
	v_cndmask_b32_e32 v2, v2, v96, vcc
	v_cndmask_b32_e32 v5, v0, v10, vcc
	v_cndmask_b32_e32 v4, v11, v12, vcc
	v_lshlrev_b64 v[2:3], 12, v[2:3]
	v_lshl_add_u64 v[2:3], v[4:5], 0, v[2:3]
	v_lshl_add_u64 v[2:3], v[2:3], 0, v[88:89]
	global_load_dwordx4 v[46:49], v[2:3], off
	global_load_dwordx4 v[42:45], v[2:3], off offset:1024
	global_load_dwordx4 v[38:41], v[2:3], off offset:2048
	global_load_dwordx4 v[34:37], v[2:3], off offset:3072
	v_cmp_gt_i32_e32 vcc, s85, v94
	v_add_u32_e32 v2, 0xffff8002, v90
	s_nop 0
	v_cndmask_b32_e32 v3, 0, v95, vcc
	v_cndmask_b32_e32 v2, v2, v94, vcc
	v_cndmask_b32_e32 v5, v0, v10, vcc
	v_cndmask_b32_e32 v4, v11, v12, vcc
	v_lshlrev_b64 v[2:3], 12, v[2:3]
	v_lshl_add_u64 v[2:3], v[4:5], 0, v[2:3]
	v_lshl_add_u64 v[2:3], v[2:3], 0, v[88:89]
	global_load_dwordx4 v[30:33], v[2:3], off
	global_load_dwordx4 v[26:29], v[2:3], off offset:1024
	global_load_dwordx4 v[14:17], v[2:3], off offset:2048
	global_load_dwordx4 v[6:9], v[2:3], off offset:3072
	v_cmp_gt_i32_e32 vcc, s85, v92
	v_add_u32_e32 v2, 0xffff8003, v90
	s_nop 0
	v_cndmask_b32_e32 v3, 0, v93, vcc
	v_cndmask_b32_e32 v2, v2, v92, vcc
	v_cndmask_b32_e32 v5, v0, v10, vcc
	v_cndmask_b32_e32 v4, v11, v12, vcc
	v_lshlrev_b64 v[2:3], 12, v[2:3]
	v_lshl_add_u64 v[2:3], v[4:5], 0, v[2:3]
	v_lshl_add_u64 v[2:3], v[2:3], 0, v[88:89]
	global_load_dwordx4 v[22:25], v[2:3], off
	global_load_dwordx4 v[18:21], v[2:3], off offset:1024
	global_load_dwordx4 v[10:13], v[2:3], off offset:2048
	s_nop 0
	global_load_dwordx4 v[2:5], v[2:3], off offset:3072
	s_waitcnt vmcnt(15)
; DI void phase0b(const Params& p, char* lds) {
;     ...
;         for (int q = 0; q < 4; ++q) {
;           const int row = rb + w * 8 + qb * 4 + q;
;           float ss = 0.f;
; #pragma unroll
;           for (int pp = 0; pp < 4; ++pp) {
;             const f32x4 v = xv[q][pp];
;             ss += (v[0] * v[0] + v[1] * v[1]) + (v[2] * v[2] + v[3] * v[3]);
;             u32x2 o;
;             o[0] = pkh2(v[0] * gsv[pp][0], v[1] * gsv[pp][1]);
;             o[1] = pkh2(v[2] * gsv[pp][2], v[3] * gsv[pp][3]);
;             *(u32x2*)(p.xg + (size_t)row * DM + pp * 256 + lane * 4) = o;
;           }
; #pragma unroll
;           for (int m = 1; m < 64; m <<= 1) ss += __shfl_xor(ss, m);
;           if (lane < 16) p.ssq[(size_t)row * 16 + lane] = (lane == 0) ? ss : 0.f;
	v_mul_f32_e32 v0, v63, v63
	v_mul_f32_e32 v89, v65, v65
	v_fmac_f32_e32 v0, v62, v62
	v_fmac_f32_e32 v89, v64, v64
	v_pk_mul_f32 v[62:63], v[68:69], v[62:63]
	v_pk_mul_f32 v[64:65], v[66:67], v[64:65]
	v_cvt_pk_f16_f32 v62, v62, v63
	v_cvt_pk_f16_f32 v63, v64, v65
	v_lshl_add_u64 v[64:65], v[86:87], 0, v[98:99]
	global_store_dwordx2 v[64:65], v[62:63], off
	s_waitcnt vmcnt(15)
	v_mul_f32_e32 v62, v59, v59
	v_mul_f32_e32 v63, v61, v61
	v_fmac_f32_e32 v62, v58, v58
	v_fmac_f32_e32 v63, v60, v60
	v_pk_mul_f32 v[58:59], v[70:71], v[58:59]
	v_pk_mul_f32 v[60:61], v[72:73], v[60:61]
	v_cvt_pk_f16_f32 v58, v58, v59
	v_cvt_pk_f16_f32 v59, v60, v61
	global_store_dwordx2 v[64:65], v[58:59], off offset:512
	s_waitcnt vmcnt(15)
	v_mul_f32_e32 v58, v55, v55
	v_mul_f32_e32 v59, v57, v57
	v_fmac_f32_e32 v58, v54, v54
	v_fmac_f32_e32 v59, v56, v56
	v_pk_mul_f32 v[54:55], v[76:77], v[54:55]
	v_pk_mul_f32 v[56:57], v[74:75], v[56:57]
	v_cvt_pk_f16_f32 v54, v54, v55
	v_cvt_pk_f16_f32 v55, v56, v57
	v_add_f32_e32 v0, v0, v89
	v_add_f32_e32 v62, v62, v63
	global_store_dwordx2 v[64:65], v[54:55], off offset:1024
	s_waitcnt vmcnt(15)
	v_mul_f32_e32 v54, v51, v51
	v_mul_f32_e32 v55, v53, v53
	v_add_f32_e32 v0, v0, v62
	v_add_f32_e32 v58, v58, v59
	v_fmac_f32_e32 v54, v50, v50
	v_fmac_f32_e32 v55, v52, v52
	v_add_f32_e32 v0, v0, v58
	v_add_f32_e32 v54, v54, v55
	v_add_f32_e32 v54, v0, v54
	v_xor_b32_e32 v0, 1, v240
	v_cmp_lt_i32_e32 vcc, v0, v241
	v_pk_mul_f32 v[50:51], v[80:81], v[50:51]
	v_pk_mul_f32 v[52:53], v[78:79], v[52:53]
	v_cndmask_b32_e32 v0, v240, v0, vcc
	v_cvt_pk_f16_f32 v50, v50, v51
	v_cvt_pk_f16_f32 v51, v52, v53
	v_lshlrev_b32_e32 v0, 2, v0
	global_store_dwordx2 v[64:65], v[50:51], off offset:1536
	ds_bpermute_b32 v50, v0, v54
	v_xor_b32_e32 v51, 2, v240
	v_cmp_lt_i32_e32 vcc, v51, v241
	s_waitcnt lgkmcnt(0)
	v_add_f32_e32 v50, v54, v50
	v_cndmask_b32_e32 v51, v240, v51, vcc
	v_lshlrev_b32_e32 v100, 2, v51
	ds_bpermute_b32 v51, v100, v50
	s_waitcnt lgkmcnt(0)
	v_add_f32_e32 v50, v50, v51
	v_xor_b32_e32 v51, 4, v240
	v_cmp_lt_i32_e32 vcc, v51, v241
	s_nop 1
	v_cndmask_b32_e32 v51, v240, v51, vcc
	v_lshlrev_b32_e32 v101, 2, v51
	ds_bpermute_b32 v51, v101, v50
	s_waitcnt lgkmcnt(0)
	v_add_f32_e32 v50, v50, v51
	v_xor_b32_e32 v51, 8, v240
	v_cmp_lt_i32_e32 vcc, v51, v241
	s_nop 1
	v_cndmask_b32_e32 v51, v240, v51, vcc
	v_lshlrev_b32_e32 v102, 2, v51
	ds_bpermute_b32 v51, v102, v50
	s_waitcnt lgkmcnt(0)
	v_add_f32_e32 v50, v50, v51
	v_xor_b32_e32 v51, 16, v240
	v_cmp_lt_i32_e32 vcc, v51, v241
	s_nop 1
	v_cndmask_b32_e32 v51, v240, v51, vcc
	v_lshlrev_b32_e32 v103, 2, v51
	ds_bpermute_b32 v51, v103, v50
	s_waitcnt lgkmcnt(0)
	v_add_f32_e32 v50, v50, v51
	v_xor_b32_e32 v51, 32, v240
	v_cmp_lt_i32_e32 vcc, v51, v241
	s_nop 1
	v_cndmask_b32_e32 v51, v240, v51, vcc
	v_lshlrev_b32_e32 v108, 2, v51
	ds_bpermute_b32 v51, v108, v50
	s_and_saveexec_b64 s[2:3], s[4:5]
	s_cbranch_execz .LBB0_19
	v_lshlrev_b64 v[52:53], 6, v[90:91]
	s_waitcnt lgkmcnt(0)
	v_add_f32_e32 v50, v50, v51
	v_lshl_add_u64 v[52:53], v[82:83], 0, v[52:53]
	v_cndmask_b32_e64 v50, 0, v50, s[6:7]
	global_store_dword v[52:53], v50, off
